# local seam completion: L1 invalidate issued up front with the arrival atomic's collection instead of after the poll
# speedup vs baseline: 1.0059x; 1.0059x over previous
.LBB0_320:
	s_andn2_b64 vcc, exec, s[0:1]
	s_cbranch_vccnz .LBB0_399
	v_bfe_i32 v2, v12, 27, 1
	v_lshlrev_b32_e32 v0, 4, v12
	v_lshrrev_b32_e32 v2, 22, v2
	v_add_u32_e32 v2, v0, v2
	v_and_b32_e32 v2, 0xfffffc00, v2
	v_sub_u32_e32 v2, v0, v2
	v_ashrrev_i32_e32 v1, 31, v12
	s_waitcnt lgkmcnt(0)
	v_lshrrev_b32_e32 v3, 4, v2
	v_lshrrev_b32_e32 v1, 26, v1
	v_bitop3_b32 v2, v3, v2, 32 bitop3:0x6c
	v_add_u32_e32 v1, v12, v1
	v_ashrrev_i32_e32 v4, 31, v2
	v_ashrrev_i32_e32 v1, 6, v1
	v_lshrrev_b32_e32 v4, 26, v4
	v_lshlrev_b32_e32 v3, 3, v1
	v_add_u32_e32 v4, v2, v4
	v_and_b32_e32 v3, -16, v3
	v_ashrrev_i32_e32 v5, 6, v4
	v_lshlrev_b32_e32 v1, 5, v1
	v_add_u32_e32 v3, v5, v3
	v_and_b32_e32 v13, 32, v1
	v_and_b32_e32 v1, 0xc0, v4
	v_sub_u32_e32 v1, v2, v1
	v_lshlrev_b32_e32 v2, 1, v3
	v_lshrrev_b32_e32 v4, 2, v3
	v_and_b32_e32 v5, 3, v5
	s_mov_b32 s1, 0x7fffffe0
	v_ashrrev_i16_sdwa v1, v155, sext(v1) dst_sel:DWORD dst_unused:UNUSED_PAD src0_sel:DWORD src1_sel:BYTE_0
	v_and_b32_e32 v2, 24, v2
	v_and_b32_e32 v4, 4, v4
	v_and_or_b32 v5, v3, s1, v5
	v_bfe_i32 v14, v1, 0, 16
	v_or3_b32 v2, v5, v4, v2
	v_readlane_b32 s52, v233, 50
	v_add_u32_e32 v1, v13, v14
	v_add_u32_e32 v0, 0x2000, v0
	v_mul_lo_u32 v15, v3, s52
	v_mul_lo_u32 v2, v2, s52
	v_add_lshl_u32 v130, v1, v15, 1
	v_add_lshl_u32 v96, v2, v1, 1
	v_ashrrev_i32_e32 v1, 31, v0
	v_lshrrev_b32_e32 v1, 22, v1
	v_add_u32_e32 v1, v0, v1
	v_ashrrev_i32_e32 v1, 10, v1
	v_readlane_b32 s53, v233, 51
	v_mul_i32_i24_e32 v2, 0x400, v1
	v_sub_u32_e32 v0, v0, v2
	s_mov_b32 s53, s47
	v_lshrrev_b32_e32 v2, 4, v0
	s_lshl_b64 s[72:73], s[52:53], 9
	s_ashr_i32 s9, s46, 31
	v_bitop3_b32 v0, v2, v0, 32 bitop3:0x6c
	s_mul_i32 s9, s72, s9
	s_mul_hi_u32 s39, s72, s46
	v_ashrrev_i32_e32 v3, 31, v0
	s_add_i32 s9, s39, s9
	s_lshr_b32 s39, s52, 23
	v_writelane_b32 v232, s76, 22
	v_lshrrev_b32_e32 v3, 26, v3
	s_mul_i32 s40, s39, s46
	v_writelane_b32 v232, s77, 23
	v_lshlrev_b32_e32 v2, 3, v1
	v_add_u32_e32 v3, v0, v3
	s_add_i32 s43, s9, s40
	s_ashr_i32 s9, s69, 31
	v_writelane_b32 v232, s78, 24
	v_and_b32_e32 v2, -16, v2
	v_ashrrev_i32_e32 v4, 6, v3
	s_mul_i32 s9, s72, s9
	s_mul_hi_u32 s40, s72, s69
	v_writelane_b32 v232, s79, 25
	s_ashr_i32 s0, s38, 6
	v_add_u32_e32 v2, v4, v2
	v_lshlrev_b32_e32 v1, 5, v1
	v_and_b32_e32 v4, 3, v4
	s_add_i32 s9, s40, s9
	s_mul_i32 s39, s39, s69
	v_and_b32_e32 v16, 32, v1
	v_and_b32_e32 v1, 0xc0, v3
	v_and_or_b32 v4, v2, s1, v4
	s_ashr_i32 s1, s38, 8
	s_lshl_b64 s[34:35], s[52:53], 8
	s_lshl_b32 s8, s0, 10
	s_add_i32 s9, s9, s39
	s_mul_i32 s39, s72, s69
	v_readlane_b32 s40, v232, 11
	v_sub_u32_e32 v0, v0, v1
	v_lshlrev_b32_e32 v1, 1, v2
	v_lshrrev_b32_e32 v3, 2, v2
	v_readlane_b32 s41, v232, 12
	s_add_u32 s78, s40, s39
	v_ashrrev_i16_sdwa v0, v155, sext(v0) dst_sel:DWORD dst_unused:UNUSED_PAD src0_sel:DWORD src1_sel:BYTE_0
	v_and_b32_e32 v1, 24, v1
	v_and_b32_e32 v3, 4, v3
	s_addc_u32 s79, s41, s9
	s_add_i32 s9, s8, 0
	v_bfe_i32 v17, v0, 0, 16
	v_or3_b32 v1, v4, v3, v1
	v_mov_b32_e32 v19, 0
	v_mov_b32_e32 v20, 0
	v_mov_b32_e32 v21, 0
	v_mov_b32_e32 v22, 0
	v_mov_b32_e32 v23, 0
	v_mov_b32_e32 v24, 0
	v_mov_b32_e32 v25, 0
	v_mov_b32_e32 v26, 0
	v_mov_b32_e32 v27, 0
	v_mov_b32_e32 v28, 0
	v_mov_b32_e32 v29, 0
	v_mov_b32_e32 v30, 0
	v_mov_b32_e32 v31, 0
	v_mov_b32_e32 v32, 0
	v_mov_b32_e32 v33, 0
	v_mov_b32_e32 v34, 0
	v_mov_b32_e32 v35, 0
	v_mov_b32_e32 v36, 0
	v_mov_b32_e32 v37, 0
	v_mov_b32_e32 v38, 0
	v_mov_b32_e32 v39, 0
	v_mov_b32_e32 v40, 0
	v_mov_b32_e32 v41, 0
	v_mov_b32_e32 v42, 0
	v_mov_b32_e32 v43, 0
	v_mov_b32_e32 v44, 0
	v_mov_b32_e32 v45, 0
	v_mov_b32_e32 v46, 0
	v_mov_b32_e32 v47, 0
	v_mov_b32_e32 v48, 0
	v_mov_b32_e32 v49, 0
	v_mov_b32_e32 v50, 0
	v_mov_b32_e32 v51, 0
	v_mov_b32_e32 v52, 0
	v_mov_b32_e32 v53, 0
	v_mov_b32_e32 v54, 0
	v_mov_b32_e32 v55, 0
	v_mov_b32_e32 v56, 0
	v_mov_b32_e32 v57, 0
	v_mov_b32_e32 v58, 0
	v_mov_b32_e32 v59, 0
	v_mov_b32_e32 v60, 0
	v_mov_b32_e32 v61, 0
	v_mov_b32_e32 v62, 0
	v_mov_b32_e32 v63, 0
	v_mov_b32_e32 v64, 0
	v_mov_b32_e32 v65, 0
	v_mov_b32_e32 v66, 0
	v_mov_b32_e32 v67, 0
	v_mov_b32_e32 v68, 0
	v_mov_b32_e32 v69, 0
	v_mov_b32_e32 v70, 0
	v_mov_b32_e32 v71, 0
	v_mov_b32_e32 v72, 0
	v_mov_b32_e32 v73, 0
	v_mov_b32_e32 v74, 0
	v_mov_b32_e32 v75, 0
	v_mov_b32_e32 v76, 0
	v_mov_b32_e32 v77, 0
	v_mov_b32_e32 v78, 0
	v_mov_b32_e32 v79, 0
	v_mov_b32_e32 v80, 0
	v_mov_b32_e32 v81, 0
	v_mov_b32_e32 v82, 0
	v_mov_b32_e32 v83, 0
	v_mov_b32_e32 v84, 0
	v_mov_b32_e32 v85, 0
	v_mov_b32_e32 v86, 0
	v_mov_b32_e32 v87, 0
	v_mov_b32_e32 v88, 0
	v_mov_b32_e32 v89, 0
	v_mov_b32_e32 v90, 0
	v_mov_b32_e32 v91, 0
	v_mov_b32_e32 v92, 0
	v_mov_b32_e32 v93, 0
	v_mov_b32_e32 v94, 0
	v_mov_b32_e32 v95, 0
	v_mov_b32_e32 v98, 0
	v_mov_b32_e32 v99, 0
	v_mov_b32_e32 v100, 0
	v_mov_b32_e32 v101, 0
	v_mov_b32_e32 v102, 0
	v_mov_b32_e32 v103, 0
	v_mov_b32_e32 v104, 0
	v_mov_b32_e32 v105, 0
	v_mov_b32_e32 v106, 0
	v_mov_b32_e32 v107, 0
	v_mov_b32_e32 v108, 0
	v_mov_b32_e32 v109, 0
	v_mov_b32_e32 v110, 0
	v_mov_b32_e32 v111, 0
	v_mov_b32_e32 v112, 0
	v_mov_b32_e32 v113, 0
	v_mov_b32_e32 v114, 0
	v_mov_b32_e32 v115, 0
	v_mov_b32_e32 v116, 0
	v_mov_b32_e32 v117, 0
	v_mov_b32_e32 v118, 0
	v_mov_b32_e32 v119, 0
	v_mov_b32_e32 v120, 0
	v_mov_b32_e32 v121, 0
	v_mov_b32_e32 v122, 0
	v_mov_b32_e32 v123, 0
	v_mov_b32_e32 v124, 0
	v_mov_b32_e32 v125, 0
	v_mov_b32_e32 v126, 0
	v_mov_b32_e32 v127, 0
	v_mov_b32_e32 v128, 0
	v_mov_b32_e32 v129, 0
	v_readlane_b32 vcc_lo, v232, 58
	s_cmp_eq_u32 vcc_lo, 0
	s_cbranch_scc1 .Lsb_done_g
	v_readfirstlane_b32 vcc_hi, v152
	s_cmp_lt_u32 vcc_hi, 64
	s_cbranch_scc0 .Lsb_wait_g
	buffer_inv sc1
	s_waitcnt vmcnt(0)
	v_readfirstlane_b32 vcc_lo, v210
	s_and_b32 vcc_hi, vcc_lo, 31
	s_cmp_eq_u32 vcc_hi, 31
	s_cbranch_scc1 .Lsb_got_g
	s_or_b32 vcc_lo, vcc_lo, 31
	s_add_u32 vcc_lo, vcc_lo, 1
	v_mov_b32_e32 v211, vcc_lo
	v_readlane_b32 s100, v234, 34
	v_readlane_b32 s101, v234, 35
	s_mov_b32 m0, 0
	s_nop 4
.Lsb_poll_g:
	global_load_dword v210, v97, s[100:101] sc1
	s_waitcnt vmcnt(0)
	v_cmp_lt_u32_e32 vcc, v210, v211
	s_cbranch_vccz .Lsb_got_g
	s_sleep 1
	s_add_u32 m0, m0, 1
	s_cmp_lt_u32 m0, 0x40000
	s_cbranch_scc1 .Lsb_poll_g
.Lsb_got_g:
	s_waitcnt vmcnt(0)
.Lsb_wait_g:
	s_mov_b32 vcc_lo, 0
	v_writelane_b32 v232, vcc_lo, 58
	s_barrier

.LBB0_486:
	s_and_b64 vcc, exec, s[0:1]
	s_cbranch_vccz .LBB0_511
	v_readlane_b32 s0, v235, 30
	v_readlane_b32 s1, v232, 21
	s_add_i32 s8, s0, s1
	v_readlane_b32 s0, v236, 8
	v_readlane_b32 s1, v236, 9
	s_and_b64 s[0:1], s[0:1], exec
	s_cselect_b32 s8, s8, s76
	s_cmp_ge_i32 s8, s98
	s_cbranch_scc1 .LBB0_511
	v_readlane_b32 vcc_lo, v232, 58
	s_cmp_eq_u32 vcc_lo, 0
	s_cbranch_scc1 .Lsb_done_r
	v_readfirstlane_b32 vcc_hi, v152
	s_cmp_lt_u32 vcc_hi, 64
	s_cbranch_scc0 .Lsb_wait_r
	buffer_inv sc1
	s_waitcnt vmcnt(0)
	v_readfirstlane_b32 vcc_lo, v210
	s_and_b32 vcc_hi, vcc_lo, 31
	s_cmp_eq_u32 vcc_hi, 31
	s_cbranch_scc1 .Lsb_got_r
	s_or_b32 vcc_lo, vcc_lo, 31
	s_add_u32 vcc_lo, vcc_lo, 1
	v_mov_b32_e32 v211, vcc_lo
	v_readlane_b32 s100, v234, 34
	v_readlane_b32 s101, v234, 35
	s_mov_b32 m0, 0
	s_nop 4
.Lsb_poll_r:
	global_load_dword v210, v97, s[100:101] sc1
	s_waitcnt vmcnt(0)
	v_cmp_lt_u32_e32 vcc, v210, v211
	s_cbranch_vccz .Lsb_got_r
	s_sleep 1
	s_add_u32 m0, m0, 1
	s_cmp_lt_u32 m0, 0x40000
	s_cbranch_scc1 .Lsb_poll_r
.Lsb_got_r:
	s_waitcnt vmcnt(0)
.Lsb_wait_r:
	s_mov_b32 vcc_lo, 0
	v_writelane_b32 v232, vcc_lo, 58
	s_barrier

.LBB0_511:
	v_readlane_b32 vcc_lo, v232, 58
	s_cmp_eq_u32 vcc_lo, 0
	s_cbranch_scc1 .Lsb_done_e
	v_readfirstlane_b32 vcc_hi, v152
	s_cmp_lt_u32 vcc_hi, 64
	s_cbranch_scc0 .Lsb_wait_e
	buffer_inv sc1
	s_waitcnt vmcnt(0)
	v_readfirstlane_b32 vcc_lo, v210
	s_and_b32 vcc_hi, vcc_lo, 31
	s_cmp_eq_u32 vcc_hi, 31
	s_cbranch_scc1 .Lsb_got_e
	s_or_b32 vcc_lo, vcc_lo, 31
	s_add_u32 vcc_lo, vcc_lo, 1
	v_mov_b32_e32 v211, vcc_lo
	v_readlane_b32 s100, v234, 34
	v_readlane_b32 s101, v234, 35
	s_mov_b32 m0, 0
	s_nop 4
.Lsb_poll_e:
	global_load_dword v210, v97, s[100:101] sc1
	s_waitcnt vmcnt(0)
	v_cmp_lt_u32_e32 vcc, v210, v211
	s_cbranch_vccz .Lsb_got_e
	s_sleep 1
	s_add_u32 m0, m0, 1
	s_cmp_lt_u32 m0, 0x40000
	s_cbranch_scc1 .Lsb_poll_e
.Lsb_got_e:
	s_waitcnt vmcnt(0)
.Lsb_wait_e:
	s_mov_b32 vcc_lo, 0
	v_writelane_b32 v232, vcc_lo, 58
	s_barrier
